# v22: v19 + SwiGLU GEMM epilogues (G1,G5): per-row ss loads issued at the top of the tile iteration (before the K loop) so the epilogue head no longer drains the next tile's LDS-DMA prefetch with vmcnt
# baseline (speedup 1.0000x reference)
;     __host__ __device__ bool next(int i, Unit& u) const {
;         const long L = (long)i * G + c; if (L >= nwg) return false;
;         int wgid = (int)L; { const int q = nwg / NXCD, r = nwg % NXCD, xcd = wgid % NXCD, off = wgid / NXCD; wgid = (xcd < r ? xcd * (q + 1) : r * (q + 1) + (xcd - r) * q) + off; }
;         const int nig = WGM * nN, gid = wgid / nig, fm = gid * WGM, gsz = (nM - fm) < WGM ? (nM - fm) : WGM;
;         u.pm = fm + ((wgid % nig) % gsz); u.pn = (wgid % nig) / gsz; u.kt0 = 0; u.nkt = nktf; u.kind = 0; u.slot = 0; return true;
;     __device__ __forceinline__ void operator()(const f32x4 (&acc)[2][2][4][2], const Unit& u, int wr, int wc, int fr, int fq) const {
;         const int row0 = u.pm * BM + wr * 64 + fr, col0 = u.pn * 128 + wc * 32 + 8 * fq;
; #pragma unroll
;         for (int ai = 0; ai < 2; ++ai)
; #pragma unroll
;             for (int m = 0; m < 4; ++m) {
;                 const int row = row0 + ai * HALF + m * 16;
;                 const float rs = rsqrtf(ss[row] * (1.f / DM) + EPS);
.LBB0_287:
	v_lshrrev_b32_e32 v138, 8, v212
	v_and_b32_e32 v139, 15, v212
	v_lshl_or_b32 v138, v138, 6, v139
	v_lshl_add_u32 v138, s41, 8, v138
	v_ashrrev_i32_e32 v139, 31, v138
	v_lshl_add_u64 v[140:141], v[138:139], 2, s[10:11]
	global_load_dword v159, v[140:141], off
	global_load_dword v213, v[140:141], off offset:64
	global_load_dword v214, v[140:141], off offset:128
	global_load_dword v215, v[140:141], off offset:192
	global_load_dword v218, v[140:141], off offset:512
	global_load_dword v222, v[140:141], off offset:576
	global_load_dword v155, v[140:141], off offset:640
	global_load_dword v157, v[140:141], off offset:704
	v_readlane_b32 s18, v254, 12
	s_add_i32 s39, s39, 1
	v_readlane_b32 s19, v254, 13
	s_mul_i32 s4, s39, s19
	s_mul_hi_u32 s5, s39, s18
	s_add_i32 s5, s5, s4
	s_mul_i32 s4, s39, s18
	v_readlane_b32 s15, v254, 0
	s_add_u32 s18, s4, s15
	v_readlane_b32 s4, v254, 9
	s_addc_u32 s19, s5, s4
	v_cmp_gt_i64_e32 vcc, s[18:19], v[148:149]
	v_cmp_lt_i64_e64 s[4:5], s[18:19], v[146:147]
	s_cbranch_vccnz .LBB0_293
	s_ashr_i32 s14, s18, 31
	s_lshr_b32 s14, s14, 29
	s_add_i32 s16, s18, s14
	s_and_b32 s14, s16, -8
	s_sub_i32 s17, s18, s14
	s_cmp_gt_i32 s17, 5
	s_mov_b64 s[14:15], -1
	s_cbranch_scc0 .LBB0_290
	s_mul_i32 s14, s17, 0xbd
	s_add_i32 s18, s14, 6
	s_mov_b64 s[14:15], 0

; DI unsigned cvt_pk(float lo, float hi) { unsigned r; asm("v_cvt_pk_bf16_f32 %0, %1, %2" : "=v"(r) : "v"(lo), "v"(hi)); return r; }
; DI float siluf_(float x) { return x * sigmoidf_(x); }
;     __device__ __forceinline__ void operator()(const f32x4 (&acc)[2][2][4][2], const Unit& u, int wr, int wc, int fr, int fq) const {
;         const int row0 = u.pm * BM + wr * 64 + fr, col0 = u.pn * 128 + wc * 32 + 8 * fq;
; #pragma unroll
;         for (int ai = 0; ai < 2; ++ai)
; #pragma unroll
;             for (int m = 0; m < 4; ++m) {
;                 const int row = row0 + ai * HALF + m * 16;
;                 const float rs = rsqrtf(ss[row] * (1.f / DM) + EPS);
;                 float h[8];
; #pragma unroll
;                 for (int n = 0; n < 2; ++n)
; #pragma unroll
;                     for (int j = 0; j < 4; ++j) { const float gg = acc[ai][0][m][n][j] * rs, uu = acc[ai][1][m][n][j] * rs; h[4 * n + j] = siluf_(gg) * uu; }
;                 u32x4 w; w.x = cvt_pk(h[0], h[1]); w.y = cvt_pk(h[2], h[3]); w.z = cvt_pk(h[4], h[5]); w.w = cvt_pk(h[6], h[7]);
;                 *(u32x4*)(H + (size_t)row * DFF + col0) = w;
;             }
.LBB0_297:
	v_lshrrev_b32_e32 v138, 8, v212
	v_and_b32_e32 v139, 15, v212
	v_lshl_or_b32 v138, v138, 6, v139
	v_lshl_add_u32 v138, s41, 8, v138
	s_mov_b32 s15, 0x800000
	v_lshrrev_b32_e32 v142, 6, v212
	v_and_b32_e32 v142, 3, v142
	v_lshrrev_b32_e32 v143, 1, v212
	v_and_b32_e32 v143, 24, v143
	v_lshl_or_b32 v142, v142, 5, v143
	v_lshl_or_b32 v142, s40, 7, v142
	v_ashrrev_i32_e32 v143, 31, v142
	v_mov_b64_e32 v[186:187], s[8:9]
	v_lshlrev_b64 v[188:189], 1, v[142:143]
	v_fmamk_f32 v180, v159, 0x3a800000, v217
	v_cmp_gt_f32_e32 vcc, s15, v180
	v_mul_f32_e32 v181, 0x4b800000, v180
	s_nop 0
	v_cndmask_b32_e32 v180, v180, v181, vcc
	v_rsq_f32_e32 v180, v180
	v_add_u32_e32 v182, 0, v138
	v_mul_f32_e32 v181, 0x45800000, v180
	v_cndmask_b32_e32 v180, v180, v181, vcc
	v_mul_f32_e32 v124, v124, v180
	v_mul_f32_e32 v120, v120, v180
	v_mul_f32_e32 v125, v125, v180
	v_mul_f32_e32 v121, v121, v180
	v_mul_f32_e32 v126, v126, v180
	v_mul_f32_e32 v122, v122, v180
	v_mul_f32_e32 v127, v127, v180
	v_mul_f32_e32 v123, v123, v180
	v_mul_f32_e32 v116, v116, v180
	v_mul_f32_e32 v112, v112, v180
	v_mul_f32_e32 v117, v117, v180
	v_mul_f32_e32 v113, v113, v180
	v_mul_f32_e32 v118, v118, v180
	v_mul_f32_e32 v114, v114, v180
	v_mul_f32_e32 v119, v119, v180
	v_mul_f32_e32 v115, v115, v180
	v_mul_f32_e32 v172, 0xbfb8aa3b, v124
	v_mul_f32_e32 v173, 0xbfb8aa3b, v125
	v_mul_f32_e32 v174, 0xbfb8aa3b, v126
	v_mul_f32_e32 v175, 0xbfb8aa3b, v127
	v_mul_f32_e32 v176, 0xbfb8aa3b, v116
	v_mul_f32_e32 v177, 0xbfb8aa3b, v117
	v_mul_f32_e32 v178, 0xbfb8aa3b, v118
	v_mul_f32_e32 v179, 0xbfb8aa3b, v119
	v_exp_f32_e32 v172, v172
	v_exp_f32_e32 v173, v173
	v_exp_f32_e32 v174, v174
	v_exp_f32_e32 v175, v175
	v_exp_f32_e32 v176, v176
	v_exp_f32_e32 v177, v177
	v_exp_f32_e32 v178, v178
	v_exp_f32_e32 v179, v179
	v_add_f32_e32 v172, 1.0, v172
	v_add_f32_e32 v173, 1.0, v173
	v_add_f32_e32 v174, 1.0, v174
	v_add_f32_e32 v175, 1.0, v175
	v_add_f32_e32 v176, 1.0, v176
	v_add_f32_e32 v177, 1.0, v177
	v_add_f32_e32 v178, 1.0, v178
	v_add_f32_e32 v179, 1.0, v179
	v_rcp_f32_e32 v172, v172
	v_rcp_f32_e32 v173, v173
	v_rcp_f32_e32 v174, v174
	v_rcp_f32_e32 v175, v175
	v_rcp_f32_e32 v176, v176
	v_rcp_f32_e32 v177, v177
	v_rcp_f32_e32 v178, v178
	v_rcp_f32_e32 v179, v179
	v_mul_f32_e32 v124, v124, v172
	v_mul_f32_e32 v125, v125, v173
	v_mul_f32_e32 v126, v126, v174
	v_mul_f32_e32 v127, v127, v175
	v_mul_f32_e32 v116, v116, v176
	v_mul_f32_e32 v117, v117, v177
	v_mul_f32_e32 v118, v118, v178
	v_mul_f32_e32 v119, v119, v179
	v_mul_f32_e32 v124, v120, v124
	v_mul_f32_e32 v125, v121, v125
	v_mul_f32_e32 v126, v122, v126
	v_mul_f32_e32 v127, v123, v127
	v_mul_f32_e32 v116, v112, v116
	v_mul_f32_e32 v117, v113, v117
	v_mul_f32_e32 v118, v114, v118
	v_mul_f32_e32 v119, v115, v119
	v_mad_i64_i32 v[184:185], s[2:3], v182, s64, v[186:187]
	v_cvt_pk_bf16_f32 v172, v124, v125
	v_cvt_pk_bf16_f32 v173, v126, v127
	v_cvt_pk_bf16_f32 v174, v116, v117
	v_cvt_pk_bf16_f32 v175, v118, v119
	v_lshl_add_u64 v[184:185], v[184:185], 0, v[188:189]
	global_store_dwordx4 v[184:185], v[172:175], off
	v_fmamk_f32 v180, v213, 0x3a800000, v217
	v_cmp_gt_f32_e32 vcc, s15, v180
	v_mul_f32_e32 v181, 0x4b800000, v180
	s_nop 0
	v_cndmask_b32_e32 v180, v180, v181, vcc
	v_rsq_f32_e32 v180, v180
	v_add_u32_e32 v182, 16, v138
	v_mul_f32_e32 v181, 0x45800000, v180
	v_cndmask_b32_e32 v180, v180, v181, vcc
	v_mul_f32_e32 v108, v108, v180
	v_mul_f32_e32 v104, v104, v180
	v_mul_f32_e32 v109, v109, v180
	v_mul_f32_e32 v105, v105, v180
	v_mul_f32_e32 v110, v110, v180
	v_mul_f32_e32 v106, v106, v180
	v_mul_f32_e32 v111, v111, v180
	v_mul_f32_e32 v107, v107, v180
	v_mul_f32_e32 v100, v100, v180
	v_mul_f32_e32 v96, v96, v180
	v_mul_f32_e32 v101, v101, v180
	v_mul_f32_e32 v97, v97, v180
	v_mul_f32_e32 v102, v102, v180
	v_mul_f32_e32 v98, v98, v180
	v_mul_f32_e32 v103, v103, v180
	v_mul_f32_e32 v99, v99, v180
	v_mul_f32_e32 v172, 0xbfb8aa3b, v108
	v_mul_f32_e32 v173, 0xbfb8aa3b, v109
	v_mul_f32_e32 v174, 0xbfb8aa3b, v110
	v_mul_f32_e32 v175, 0xbfb8aa3b, v111
	v_mul_f32_e32 v176, 0xbfb8aa3b, v100
	v_mul_f32_e32 v177, 0xbfb8aa3b, v101
	v_mul_f32_e32 v178, 0xbfb8aa3b, v102
	v_mul_f32_e32 v179, 0xbfb8aa3b, v103
	v_exp_f32_e32 v172, v172
	v_exp_f32_e32 v173, v173
	v_exp_f32_e32 v174, v174
	v_exp_f32_e32 v175, v175
	v_exp_f32_e32 v176, v176
	v_exp_f32_e32 v177, v177
	v_exp_f32_e32 v178, v178
	v_exp_f32_e32 v179, v179
	v_add_f32_e32 v172, 1.0, v172
	v_add_f32_e32 v173, 1.0, v173
	v_add_f32_e32 v174, 1.0, v174
	v_add_f32_e32 v175, 1.0, v175
	v_add_f32_e32 v176, 1.0, v176
	v_add_f32_e32 v177, 1.0, v177
	v_add_f32_e32 v178, 1.0, v178
	v_add_f32_e32 v179, 1.0, v179
	v_rcp_f32_e32 v172, v172
	v_rcp_f32_e32 v173, v173
	v_rcp_f32_e32 v174, v174
	v_rcp_f32_e32 v175, v175
	v_rcp_f32_e32 v176, v176
	v_rcp_f32_e32 v177, v177
	v_rcp_f32_e32 v178, v178
	v_rcp_f32_e32 v179, v179
	v_mul_f32_e32 v108, v108, v172
	v_mul_f32_e32 v109, v109, v173
	v_mul_f32_e32 v110, v110, v174
	v_mul_f32_e32 v111, v111, v175
	v_mul_f32_e32 v100, v100, v176
	v_mul_f32_e32 v101, v101, v177
	v_mul_f32_e32 v102, v102, v178
	v_mul_f32_e32 v103, v103, v179
	v_mul_f32_e32 v108, v104, v108
	v_mul_f32_e32 v109, v105, v109
	v_mul_f32_e32 v110, v106, v110
	v_mul_f32_e32 v111, v107, v111
	v_mul_f32_e32 v100, v96, v100
	v_mul_f32_e32 v101, v97, v101
	v_mul_f32_e32 v102, v98, v102
	v_mul_f32_e32 v103, v99, v103
	v_mad_i64_i32 v[184:185], s[2:3], v182, s64, v[186:187]
	v_cvt_pk_bf16_f32 v172, v108, v109
	v_cvt_pk_bf16_f32 v173, v110, v111
	v_cvt_pk_bf16_f32 v174, v100, v101
	v_cvt_pk_bf16_f32 v175, v102, v103
	v_lshl_add_u64 v[184:185], v[184:185], 0, v[188:189]
	global_store_dwordx4 v[184:185], v[172:175], off
; DI unsigned cvt_pk(float lo, float hi) { unsigned r; asm("v_cvt_pk_bf16_f32 %0, %1, %2" : "=v"(r) : "v"(lo), "v"(hi)); return r; }
; DI float siluf_(float x) { return x * sigmoidf_(x); }
;     __device__ __forceinline__ void operator()(const f32x4 (&acc)[2][2][4][2], const Unit& u, int wr, int wc, int fr, int fq) const {
;         const int row0 = u.pm * BM + wr * 64 + fr, col0 = u.pn * 128 + wc * 32 + 8 * fq;
; #pragma unroll
;         for (int ai = 0; ai < 2; ++ai)
; #pragma unroll
;             for (int m = 0; m < 4; ++m) {
;                 const int row = row0 + ai * HALF + m * 16;
;                 const float rs = rsqrtf(ss[row] * (1.f / DM) + EPS);
;                 float h[8];
; #pragma unroll
;                 for (int n = 0; n < 2; ++n)
; #pragma unroll
;                     for (int j = 0; j < 4; ++j) { const float gg = acc[ai][0][m][n][j] * rs, uu = acc[ai][1][m][n][j] * rs; h[4 * n + j] = siluf_(gg) * uu; }
;                 u32x4 w; w.x = cvt_pk(h[0], h[1]); w.y = cvt_pk(h[2], h[3]); w.z = cvt_pk(h[4], h[5]); w.w = cvt_pk(h[6], h[7]);
;                 *(u32x4*)(H + (size_t)row * DFF + col0) = w;
;             }
	v_fmamk_f32 v180, v214, 0x3a800000, v217
	v_cmp_gt_f32_e32 vcc, s15, v180
	v_mul_f32_e32 v181, 0x4b800000, v180
	s_nop 0
	v_cndmask_b32_e32 v180, v180, v181, vcc
	v_rsq_f32_e32 v180, v180
	v_add_u32_e32 v182, 32, v138
	v_mul_f32_e32 v181, 0x45800000, v180
	v_cndmask_b32_e32 v180, v180, v181, vcc
	v_mul_f32_e32 v92, v92, v180
	v_mul_f32_e32 v88, v88, v180
	v_mul_f32_e32 v93, v93, v180
	v_mul_f32_e32 v89, v89, v180
	v_mul_f32_e32 v94, v94, v180
	v_mul_f32_e32 v90, v90, v180
	v_mul_f32_e32 v95, v95, v180
	v_mul_f32_e32 v91, v91, v180
	v_mul_f32_e32 v84, v84, v180
	v_mul_f32_e32 v80, v80, v180
	v_mul_f32_e32 v85, v85, v180
	v_mul_f32_e32 v81, v81, v180
	v_mul_f32_e32 v86, v86, v180
	v_mul_f32_e32 v82, v82, v180
	v_mul_f32_e32 v87, v87, v180
	v_mul_f32_e32 v83, v83, v180
	v_mul_f32_e32 v172, 0xbfb8aa3b, v92
	v_mul_f32_e32 v173, 0xbfb8aa3b, v93
	v_mul_f32_e32 v174, 0xbfb8aa3b, v94
	v_mul_f32_e32 v175, 0xbfb8aa3b, v95
	v_mul_f32_e32 v176, 0xbfb8aa3b, v84
	v_mul_f32_e32 v177, 0xbfb8aa3b, v85
	v_mul_f32_e32 v178, 0xbfb8aa3b, v86
	v_mul_f32_e32 v179, 0xbfb8aa3b, v87
	v_exp_f32_e32 v172, v172
	v_exp_f32_e32 v173, v173
	v_exp_f32_e32 v174, v174
	v_exp_f32_e32 v175, v175
	v_exp_f32_e32 v176, v176
	v_exp_f32_e32 v177, v177
	v_exp_f32_e32 v178, v178
	v_exp_f32_e32 v179, v179
	v_add_f32_e32 v172, 1.0, v172
	v_add_f32_e32 v173, 1.0, v173
	v_add_f32_e32 v174, 1.0, v174
	v_add_f32_e32 v175, 1.0, v175
	v_add_f32_e32 v176, 1.0, v176
	v_add_f32_e32 v177, 1.0, v177
	v_add_f32_e32 v178, 1.0, v178
	v_add_f32_e32 v179, 1.0, v179
	v_rcp_f32_e32 v172, v172
	v_rcp_f32_e32 v173, v173
	v_rcp_f32_e32 v174, v174
	v_rcp_f32_e32 v175, v175
	v_rcp_f32_e32 v176, v176
	v_rcp_f32_e32 v177, v177
	v_rcp_f32_e32 v178, v178
	v_rcp_f32_e32 v179, v179
	v_mul_f32_e32 v92, v92, v172
	v_mul_f32_e32 v93, v93, v173
	v_mul_f32_e32 v94, v94, v174
	v_mul_f32_e32 v95, v95, v175
	v_mul_f32_e32 v84, v84, v176
	v_mul_f32_e32 v85, v85, v177
	v_mul_f32_e32 v86, v86, v178
	v_mul_f32_e32 v87, v87, v179
	v_mul_f32_e32 v92, v88, v92
	v_mul_f32_e32 v93, v89, v93
	v_mul_f32_e32 v94, v90, v94
	v_mul_f32_e32 v95, v91, v95
	v_mul_f32_e32 v84, v80, v84
	v_mul_f32_e32 v85, v81, v85
	v_mul_f32_e32 v86, v82, v86
	v_mul_f32_e32 v87, v83, v87
	v_mad_i64_i32 v[184:185], s[2:3], v182, s64, v[186:187]
	v_cvt_pk_bf16_f32 v172, v92, v93
	v_cvt_pk_bf16_f32 v173, v94, v95
	v_cvt_pk_bf16_f32 v174, v84, v85
	v_cvt_pk_bf16_f32 v175, v86, v87
	v_lshl_add_u64 v[184:185], v[184:185], 0, v[188:189]
	global_store_dwordx4 v[184:185], v[172:175], off
	v_fmamk_f32 v180, v215, 0x3a800000, v217
	v_cmp_gt_f32_e32 vcc, s15, v180
	v_mul_f32_e32 v181, 0x4b800000, v180
	s_nop 0
	v_cndmask_b32_e32 v180, v180, v181, vcc
	v_rsq_f32_e32 v180, v180
	v_add_u32_e32 v182, 48, v138
	v_mul_f32_e32 v181, 0x45800000, v180
	v_cndmask_b32_e32 v180, v180, v181, vcc
	v_mul_f32_e32 v76, v76, v180
	v_mul_f32_e32 v72, v72, v180
	v_mul_f32_e32 v77, v77, v180
	v_mul_f32_e32 v73, v73, v180
	v_mul_f32_e32 v78, v78, v180
	v_mul_f32_e32 v74, v74, v180
	v_mul_f32_e32 v79, v79, v180
	v_mul_f32_e32 v75, v75, v180
	v_mul_f32_e32 v68, v68, v180
	v_mul_f32_e32 v64, v64, v180
	v_mul_f32_e32 v69, v69, v180
	v_mul_f32_e32 v65, v65, v180
	v_mul_f32_e32 v70, v70, v180
	v_mul_f32_e32 v66, v66, v180
	v_mul_f32_e32 v71, v71, v180
	v_mul_f32_e32 v67, v67, v180
	v_mul_f32_e32 v172, 0xbfb8aa3b, v76
	v_mul_f32_e32 v173, 0xbfb8aa3b, v77
	v_mul_f32_e32 v174, 0xbfb8aa3b, v78
	v_mul_f32_e32 v175, 0xbfb8aa3b, v79
	v_mul_f32_e32 v176, 0xbfb8aa3b, v68
	v_mul_f32_e32 v177, 0xbfb8aa3b, v69
	v_mul_f32_e32 v178, 0xbfb8aa3b, v70
	v_mul_f32_e32 v179, 0xbfb8aa3b, v71
	v_exp_f32_e32 v172, v172
	v_exp_f32_e32 v173, v173
	v_exp_f32_e32 v174, v174
	v_exp_f32_e32 v175, v175
	v_exp_f32_e32 v176, v176
	v_exp_f32_e32 v177, v177
	v_exp_f32_e32 v178, v178
	v_exp_f32_e32 v179, v179
	v_add_f32_e32 v172, 1.0, v172
	v_add_f32_e32 v173, 1.0, v173
	v_add_f32_e32 v174, 1.0, v174
	v_add_f32_e32 v175, 1.0, v175
	v_add_f32_e32 v176, 1.0, v176
	v_add_f32_e32 v177, 1.0, v177
	v_add_f32_e32 v178, 1.0, v178
	v_add_f32_e32 v179, 1.0, v179
	v_rcp_f32_e32 v172, v172
	v_rcp_f32_e32 v173, v173
	v_rcp_f32_e32 v174, v174
	v_rcp_f32_e32 v175, v175
	v_rcp_f32_e32 v176, v176
	v_rcp_f32_e32 v177, v177
	v_rcp_f32_e32 v178, v178
	v_rcp_f32_e32 v179, v179
	v_mul_f32_e32 v76, v76, v172
	v_mul_f32_e32 v77, v77, v173
	v_mul_f32_e32 v78, v78, v174
	v_mul_f32_e32 v79, v79, v175
	v_mul_f32_e32 v68, v68, v176
	v_mul_f32_e32 v69, v69, v177
	v_mul_f32_e32 v70, v70, v178
	v_mul_f32_e32 v71, v71, v179
	v_mul_f32_e32 v76, v72, v76
	v_mul_f32_e32 v77, v73, v77
	v_mul_f32_e32 v78, v74, v78
	v_mul_f32_e32 v79, v75, v79
	v_mul_f32_e32 v68, v64, v68
	v_mul_f32_e32 v69, v65, v69
	v_mul_f32_e32 v70, v66, v70
	v_mul_f32_e32 v71, v67, v71
	v_mad_i64_i32 v[184:185], s[2:3], v182, s64, v[186:187]
	v_cvt_pk_bf16_f32 v172, v76, v77
	v_cvt_pk_bf16_f32 v173, v78, v79
	v_cvt_pk_bf16_f32 v174, v68, v69
	v_cvt_pk_bf16_f32 v175, v70, v71
	v_lshl_add_u64 v[184:185], v[184:185], 0, v[188:189]
	global_store_dwordx4 v[184:185], v[172:175], off
	v_fmamk_f32 v180, v218, 0x3a800000, v217
	v_cmp_gt_f32_e32 vcc, s15, v180
	v_mul_f32_e32 v181, 0x4b800000, v180
	s_nop 0
	v_cndmask_b32_e32 v180, v180, v181, vcc
	v_rsq_f32_e32 v180, v180
	v_add_u32_e32 v182, 128, v138
	v_mul_f32_e32 v181, 0x45800000, v180
	v_cndmask_b32_e32 v180, v180, v181, vcc
	v_mul_f32_e32 v60, v60, v180
	v_mul_f32_e32 v56, v56, v180
	v_mul_f32_e32 v61, v61, v180
	v_mul_f32_e32 v57, v57, v180
	v_mul_f32_e32 v62, v62, v180
	v_mul_f32_e32 v58, v58, v180
	v_mul_f32_e32 v63, v63, v180
	v_mul_f32_e32 v59, v59, v180
	v_mul_f32_e32 v52, v52, v180
	v_mul_f32_e32 v48, v48, v180
	v_mul_f32_e32 v53, v53, v180
; DI unsigned cvt_pk(float lo, float hi) { unsigned r; asm("v_cvt_pk_bf16_f32 %0, %1, %2" : "=v"(r) : "v"(lo), "v"(hi)); return r; }
; DI float siluf_(float x) { return x * sigmoidf_(x); }
;     __device__ __forceinline__ void operator()(const f32x4 (&acc)[2][2][4][2], const Unit& u, int wr, int wc, int fr, int fq) const {
;         const int row0 = u.pm * BM + wr * 64 + fr, col0 = u.pn * 128 + wc * 32 + 8 * fq;
; #pragma unroll
;         for (int ai = 0; ai < 2; ++ai)
; #pragma unroll
;             for (int m = 0; m < 4; ++m) {
;                 const int row = row0 + ai * HALF + m * 16;
;                 const float rs = rsqrtf(ss[row] * (1.f / DM) + EPS);
;                 float h[8];
; #pragma unroll
;                 for (int n = 0; n < 2; ++n)
; #pragma unroll
;                     for (int j = 0; j < 4; ++j) { const float gg = acc[ai][0][m][n][j] * rs, uu = acc[ai][1][m][n][j] * rs; h[4 * n + j] = siluf_(gg) * uu; }
;                 u32x4 w; w.x = cvt_pk(h[0], h[1]); w.y = cvt_pk(h[2], h[3]); w.z = cvt_pk(h[4], h[5]); w.w = cvt_pk(h[6], h[7]);
;                 *(u32x4*)(H + (size_t)row * DFF + col0) = w;
;             }
	v_mul_f32_e32 v49, v49, v180
	v_mul_f32_e32 v54, v54, v180
	v_mul_f32_e32 v50, v50, v180
	v_mul_f32_e32 v55, v55, v180
	v_mul_f32_e32 v51, v51, v180
	v_mul_f32_e32 v172, 0xbfb8aa3b, v60
	v_mul_f32_e32 v173, 0xbfb8aa3b, v61
	v_mul_f32_e32 v174, 0xbfb8aa3b, v62
	v_mul_f32_e32 v175, 0xbfb8aa3b, v63
	v_mul_f32_e32 v176, 0xbfb8aa3b, v52
	v_mul_f32_e32 v177, 0xbfb8aa3b, v53
	v_mul_f32_e32 v178, 0xbfb8aa3b, v54
	v_mul_f32_e32 v179, 0xbfb8aa3b, v55
	v_exp_f32_e32 v172, v172
	v_exp_f32_e32 v173, v173
	v_exp_f32_e32 v174, v174
	v_exp_f32_e32 v175, v175
	v_exp_f32_e32 v176, v176
	v_exp_f32_e32 v177, v177
	v_exp_f32_e32 v178, v178
	v_exp_f32_e32 v179, v179
	v_add_f32_e32 v172, 1.0, v172
	v_add_f32_e32 v173, 1.0, v173
	v_add_f32_e32 v174, 1.0, v174
	v_add_f32_e32 v175, 1.0, v175
	v_add_f32_e32 v176, 1.0, v176
	v_add_f32_e32 v177, 1.0, v177
	v_add_f32_e32 v178, 1.0, v178
	v_add_f32_e32 v179, 1.0, v179
	v_rcp_f32_e32 v172, v172
	v_rcp_f32_e32 v173, v173
	v_rcp_f32_e32 v174, v174
	v_rcp_f32_e32 v175, v175
	v_rcp_f32_e32 v176, v176
	v_rcp_f32_e32 v177, v177
	v_rcp_f32_e32 v178, v178
	v_rcp_f32_e32 v179, v179
	v_mul_f32_e32 v60, v60, v172
	v_mul_f32_e32 v61, v61, v173
	v_mul_f32_e32 v62, v62, v174
	v_mul_f32_e32 v63, v63, v175
	v_mul_f32_e32 v52, v52, v176
	v_mul_f32_e32 v53, v53, v177
	v_mul_f32_e32 v54, v54, v178
	v_mul_f32_e32 v55, v55, v179
	v_mul_f32_e32 v60, v56, v60
	v_mul_f32_e32 v61, v57, v61
	v_mul_f32_e32 v62, v58, v62
	v_mul_f32_e32 v63, v59, v63
	v_mul_f32_e32 v52, v48, v52
	v_mul_f32_e32 v53, v49, v53
	v_mul_f32_e32 v54, v50, v54
	v_mul_f32_e32 v55, v51, v55
	v_mad_i64_i32 v[184:185], s[2:3], v182, s64, v[186:187]
	v_cvt_pk_bf16_f32 v172, v60, v61
	v_cvt_pk_bf16_f32 v173, v62, v63
	v_cvt_pk_bf16_f32 v174, v52, v53
	v_cvt_pk_bf16_f32 v175, v54, v55
	v_lshl_add_u64 v[184:185], v[184:185], 0, v[188:189]
	global_store_dwordx4 v[184:185], v[172:175], off
	v_fmamk_f32 v180, v222, 0x3a800000, v217
	v_cmp_gt_f32_e32 vcc, s15, v180
	v_mul_f32_e32 v181, 0x4b800000, v180
	s_nop 0
	v_cndmask_b32_e32 v180, v180, v181, vcc
	v_rsq_f32_e32 v180, v180
	v_add_u32_e32 v182, 144, v138
	v_mul_f32_e32 v181, 0x45800000, v180
	v_cndmask_b32_e32 v180, v180, v181, vcc
	v_mul_f32_e32 v44, v44, v180
	v_mul_f32_e32 v40, v40, v180
	v_mul_f32_e32 v45, v45, v180
	v_mul_f32_e32 v41, v41, v180
	v_mul_f32_e32 v46, v46, v180
	v_mul_f32_e32 v42, v42, v180
	v_mul_f32_e32 v47, v47, v180
	v_mul_f32_e32 v43, v43, v180
	v_mul_f32_e32 v36, v36, v180
	v_mul_f32_e32 v32, v32, v180
	v_mul_f32_e32 v37, v37, v180
	v_mul_f32_e32 v33, v33, v180
	v_mul_f32_e32 v38, v38, v180
	v_mul_f32_e32 v34, v34, v180
	v_mul_f32_e32 v39, v39, v180
	v_mul_f32_e32 v35, v35, v180
	v_mul_f32_e32 v172, 0xbfb8aa3b, v44
	v_mul_f32_e32 v173, 0xbfb8aa3b, v45
	v_mul_f32_e32 v174, 0xbfb8aa3b, v46
	v_mul_f32_e32 v175, 0xbfb8aa3b, v47
	v_mul_f32_e32 v176, 0xbfb8aa3b, v36
	v_mul_f32_e32 v177, 0xbfb8aa3b, v37
	v_mul_f32_e32 v178, 0xbfb8aa3b, v38
	v_mul_f32_e32 v179, 0xbfb8aa3b, v39
	v_exp_f32_e32 v172, v172
	v_exp_f32_e32 v173, v173
	v_exp_f32_e32 v174, v174
	v_exp_f32_e32 v175, v175
	v_exp_f32_e32 v176, v176
	v_exp_f32_e32 v177, v177
	v_exp_f32_e32 v178, v178
	v_exp_f32_e32 v179, v179
	v_add_f32_e32 v172, 1.0, v172
	v_add_f32_e32 v173, 1.0, v173
	v_add_f32_e32 v174, 1.0, v174
	v_add_f32_e32 v175, 1.0, v175
	v_add_f32_e32 v176, 1.0, v176
	v_add_f32_e32 v177, 1.0, v177
	v_add_f32_e32 v178, 1.0, v178
	v_add_f32_e32 v179, 1.0, v179
	v_rcp_f32_e32 v172, v172
	v_rcp_f32_e32 v173, v173
	v_rcp_f32_e32 v174, v174
	v_rcp_f32_e32 v175, v175
	v_rcp_f32_e32 v176, v176
	v_rcp_f32_e32 v177, v177
	v_rcp_f32_e32 v178, v178
	v_rcp_f32_e32 v179, v179
	v_mul_f32_e32 v44, v44, v172
	v_mul_f32_e32 v45, v45, v173
	v_mul_f32_e32 v46, v46, v174
	v_mul_f32_e32 v47, v47, v175
	v_mul_f32_e32 v36, v36, v176
	v_mul_f32_e32 v37, v37, v177
	v_mul_f32_e32 v38, v38, v178
	v_mul_f32_e32 v39, v39, v179
	v_mul_f32_e32 v44, v40, v44
	v_mul_f32_e32 v45, v41, v45
	v_mul_f32_e32 v46, v42, v46
	v_mul_f32_e32 v47, v43, v47
	v_mul_f32_e32 v36, v32, v36
	v_mul_f32_e32 v37, v33, v37
	v_mul_f32_e32 v38, v34, v38
	v_mul_f32_e32 v39, v35, v39
	v_mad_i64_i32 v[184:185], s[2:3], v182, s64, v[186:187]
	v_cvt_pk_bf16_f32 v172, v44, v45
	v_cvt_pk_bf16_f32 v173, v46, v47
	v_cvt_pk_bf16_f32 v174, v36, v37
	v_cvt_pk_bf16_f32 v175, v38, v39
	v_lshl_add_u64 v[184:185], v[184:185], 0, v[188:189]
	global_store_dwordx4 v[184:185], v[172:175], off
	v_fmamk_f32 v180, v155, 0x3a800000, v217
	v_cmp_gt_f32_e32 vcc, s15, v180
	v_mul_f32_e32 v181, 0x4b800000, v180
	s_nop 0
	v_cndmask_b32_e32 v180, v180, v181, vcc
	v_rsq_f32_e32 v180, v180
	v_add_u32_e32 v182, 160, v138
	v_mul_f32_e32 v181, 0x45800000, v180
	v_cndmask_b32_e32 v180, v180, v181, vcc
	v_mul_f32_e32 v28, v28, v180
	v_mul_f32_e32 v24, v24, v180
; DI unsigned cvt_pk(float lo, float hi) { unsigned r; asm("v_cvt_pk_bf16_f32 %0, %1, %2" : "=v"(r) : "v"(lo), "v"(hi)); return r; }
; DI float siluf_(float x) { return x * sigmoidf_(x); }
;     __device__ __forceinline__ void operator()(const f32x4 (&acc)[2][2][4][2], const Unit& u, int wr, int wc, int fr, int fq) const {
;         const int row0 = u.pm * BM + wr * 64 + fr, col0 = u.pn * 128 + wc * 32 + 8 * fq;
; #pragma unroll
;         for (int ai = 0; ai < 2; ++ai)
; #pragma unroll
;             for (int m = 0; m < 4; ++m) {
;                 const int row = row0 + ai * HALF + m * 16;
;                 const float rs = rsqrtf(ss[row] * (1.f / DM) + EPS);
;                 float h[8];
; #pragma unroll
;                 for (int n = 0; n < 2; ++n)
; #pragma unroll
;                     for (int j = 0; j < 4; ++j) { const float gg = acc[ai][0][m][n][j] * rs, uu = acc[ai][1][m][n][j] * rs; h[4 * n + j] = siluf_(gg) * uu; }
;                 u32x4 w; w.x = cvt_pk(h[0], h[1]); w.y = cvt_pk(h[2], h[3]); w.z = cvt_pk(h[4], h[5]); w.w = cvt_pk(h[6], h[7]);
;                 *(u32x4*)(H + (size_t)row * DFF + col0) = w;
;             }
	v_mul_f32_e32 v29, v29, v180
	v_mul_f32_e32 v25, v25, v180
	v_mul_f32_e32 v30, v30, v180
	v_mul_f32_e32 v26, v26, v180
	v_mul_f32_e32 v31, v31, v180
	v_mul_f32_e32 v27, v27, v180
	v_mul_f32_e32 v20, v20, v180
	v_mul_f32_e32 v16, v16, v180
	v_mul_f32_e32 v21, v21, v180
	v_mul_f32_e32 v17, v17, v180
	v_mul_f32_e32 v22, v22, v180
	v_mul_f32_e32 v18, v18, v180
	v_mul_f32_e32 v23, v23, v180
	v_mul_f32_e32 v19, v19, v180
	v_mul_f32_e32 v172, 0xbfb8aa3b, v28
	v_mul_f32_e32 v173, 0xbfb8aa3b, v29
	v_mul_f32_e32 v174, 0xbfb8aa3b, v30
	v_mul_f32_e32 v175, 0xbfb8aa3b, v31
	v_mul_f32_e32 v176, 0xbfb8aa3b, v20
	v_mul_f32_e32 v177, 0xbfb8aa3b, v21
	v_mul_f32_e32 v178, 0xbfb8aa3b, v22
	v_mul_f32_e32 v179, 0xbfb8aa3b, v23
	v_exp_f32_e32 v172, v172
	v_exp_f32_e32 v173, v173
	v_exp_f32_e32 v174, v174
	v_exp_f32_e32 v175, v175
	v_exp_f32_e32 v176, v176
	v_exp_f32_e32 v177, v177
	v_exp_f32_e32 v178, v178
	v_exp_f32_e32 v179, v179
	v_add_f32_e32 v172, 1.0, v172
	v_add_f32_e32 v173, 1.0, v173
	v_add_f32_e32 v174, 1.0, v174
	v_add_f32_e32 v175, 1.0, v175
	v_add_f32_e32 v176, 1.0, v176
	v_add_f32_e32 v177, 1.0, v177
	v_add_f32_e32 v178, 1.0, v178
	v_add_f32_e32 v179, 1.0, v179
	v_rcp_f32_e32 v172, v172
	v_rcp_f32_e32 v173, v173
	v_rcp_f32_e32 v174, v174
	v_rcp_f32_e32 v175, v175
	v_rcp_f32_e32 v176, v176
	v_rcp_f32_e32 v177, v177
	v_rcp_f32_e32 v178, v178
	v_rcp_f32_e32 v179, v179
	v_mul_f32_e32 v28, v28, v172
	v_mul_f32_e32 v29, v29, v173
	v_mul_f32_e32 v30, v30, v174
	v_mul_f32_e32 v31, v31, v175
	v_mul_f32_e32 v20, v20, v176
	v_mul_f32_e32 v21, v21, v177
	v_mul_f32_e32 v22, v22, v178
	v_mul_f32_e32 v23, v23, v179
	v_mul_f32_e32 v28, v24, v28
	v_mul_f32_e32 v29, v25, v29
	v_mul_f32_e32 v30, v26, v30
	v_mul_f32_e32 v31, v27, v31
	v_mul_f32_e32 v20, v16, v20
	v_mul_f32_e32 v21, v17, v21
	v_mul_f32_e32 v22, v18, v22
	v_mul_f32_e32 v23, v19, v23
	v_mad_i64_i32 v[184:185], s[2:3], v182, s64, v[186:187]
	v_cvt_pk_bf16_f32 v172, v28, v29
	v_cvt_pk_bf16_f32 v173, v30, v31
	v_cvt_pk_bf16_f32 v174, v20, v21
	v_cvt_pk_bf16_f32 v175, v22, v23
	v_lshl_add_u64 v[184:185], v[184:185], 0, v[188:189]
	global_store_dwordx4 v[184:185], v[172:175], off
	v_fmamk_f32 v180, v157, 0x3a800000, v217
	v_cmp_gt_f32_e32 vcc, s15, v180
	v_mul_f32_e32 v181, 0x4b800000, v180
	s_nop 0
	v_cndmask_b32_e32 v180, v180, v181, vcc
	v_rsq_f32_e32 v180, v180
	v_add_u32_e32 v182, 176, v138
	v_mul_f32_e32 v181, 0x45800000, v180
	v_cndmask_b32_e32 v180, v180, v181, vcc
	v_mul_f32_e32 v12, v12, v180
	v_mul_f32_e32 v8, v8, v180
	v_mul_f32_e32 v13, v13, v180
	v_mul_f32_e32 v9, v9, v180
	v_mul_f32_e32 v14, v14, v180
	v_mul_f32_e32 v10, v10, v180
	v_mul_f32_e32 v15, v15, v180
	v_mul_f32_e32 v11, v11, v180
	v_mul_f32_e32 v4, v4, v180
	v_mul_f32_e32 v0, v0, v180
	v_mul_f32_e32 v5, v5, v180
	v_mul_f32_e32 v1, v1, v180
	v_mul_f32_e32 v6, v6, v180
	v_mul_f32_e32 v2, v2, v180
	v_mul_f32_e32 v7, v7, v180
	v_mul_f32_e32 v3, v3, v180
	v_mul_f32_e32 v172, 0xbfb8aa3b, v12
	v_mul_f32_e32 v173, 0xbfb8aa3b, v13
	v_mul_f32_e32 v174, 0xbfb8aa3b, v14
	v_mul_f32_e32 v175, 0xbfb8aa3b, v15
	v_mul_f32_e32 v176, 0xbfb8aa3b, v4
	v_mul_f32_e32 v177, 0xbfb8aa3b, v5
	v_mul_f32_e32 v178, 0xbfb8aa3b, v6
	v_mul_f32_e32 v179, 0xbfb8aa3b, v7
	v_exp_f32_e32 v172, v172
	v_exp_f32_e32 v173, v173
	v_exp_f32_e32 v174, v174
	v_exp_f32_e32 v175, v175
	v_exp_f32_e32 v176, v176
	v_exp_f32_e32 v177, v177
	v_exp_f32_e32 v178, v178
	v_exp_f32_e32 v179, v179
	v_add_f32_e32 v172, 1.0, v172
	v_add_f32_e32 v173, 1.0, v173
	v_add_f32_e32 v174, 1.0, v174
	v_add_f32_e32 v175, 1.0, v175
	v_add_f32_e32 v176, 1.0, v176
	v_add_f32_e32 v177, 1.0, v177
	v_add_f32_e32 v178, 1.0, v178
	v_add_f32_e32 v179, 1.0, v179
	v_rcp_f32_e32 v172, v172
	v_rcp_f32_e32 v173, v173
	v_rcp_f32_e32 v174, v174
	v_rcp_f32_e32 v175, v175
	v_rcp_f32_e32 v176, v176
	v_rcp_f32_e32 v177, v177
	v_rcp_f32_e32 v178, v178
	v_rcp_f32_e32 v179, v179
	v_mul_f32_e32 v12, v12, v172
	v_mul_f32_e32 v13, v13, v173
	v_mul_f32_e32 v14, v14, v174
	v_mul_f32_e32 v15, v15, v175
	v_mul_f32_e32 v4, v4, v176
	v_mul_f32_e32 v5, v5, v177
	v_mul_f32_e32 v6, v6, v178
	v_mul_f32_e32 v7, v7, v179
	v_mul_f32_e32 v12, v8, v12
	v_mul_f32_e32 v13, v9, v13
	v_mul_f32_e32 v14, v10, v14
	v_mul_f32_e32 v15, v11, v15
	v_mul_f32_e32 v4, v0, v4
	v_mul_f32_e32 v5, v1, v5
	v_mul_f32_e32 v6, v2, v6
	v_mul_f32_e32 v7, v3, v7
	v_mad_i64_i32 v[184:185], s[2:3], v182, s64, v[186:187]
	v_cvt_pk_bf16_f32 v172, v12, v13
	v_cvt_pk_bf16_f32 v173, v14, v15
	v_cvt_pk_bf16_f32 v174, v4, v5
	v_cvt_pk_bf16_f32 v175, v6, v7
	v_lshl_add_u64 v[184:185], v[184:185], 0, v[188:189]
	global_store_dwordx4 v[184:185], v[172:175], off
	s_mov_b64 s[2:3], -1
	s_andn2_b64 vcc, exec, s[4:5]
	s_cbranch_vccnz .LBB0_286
	s_andn2_b64 vcc, exec, s[6:7]
	s_cbranch_vccnz .LBB0_285
	s_barrier
	s_branch .LBB0_285

;     __host__ __device__ bool next(int i, Unit& u) const {
;         const long L = (long)i * G + c; if (L >= nwg) return false;
;         int wgid = (int)L; { const int q = nwg / NXCD, r = nwg % NXCD, xcd = wgid % NXCD, off = wgid / NXCD; wgid = (xcd < r ? xcd * (q + 1) : r * (q + 1) + (xcd - r) * q) + off; }
;         const int nig = WGM * nN, gid = wgid / nig, fm = gid * WGM, gsz = (nM - fm) < WGM ? (nM - fm) : WGM;
;         u.pm = fm + ((wgid % nig) % gsz); u.pn = (wgid % nig) / gsz; u.kt0 = 0; u.nkt = nktf; u.kind = 0; u.slot = 0; return true;
;     __device__ __forceinline__ void operator()(const f32x4 (&acc)[2][2][4][2], const Unit& u, int wr, int wc, int fr, int fq) const {
;         const int row0 = u.pm * BM + wr * 64 + fr, col0 = u.pn * 128 + wc * 32 + 8 * fq;
; #pragma unroll
;         for (int ai = 0; ai < 2; ++ai)
; #pragma unroll
;             for (int m = 0; m < 4; ++m) {
;                 const int row = row0 + ai * HALF + m * 16;
;                 const float rs = rsqrtf(ss[row] * (1.f / DM) + EPS);
.LBB0_1288:
	v_lshrrev_b32_e32 v138, 8, v212
	v_and_b32_e32 v139, 15, v212
	v_lshl_or_b32 v138, v138, 6, v139
	v_lshl_add_u32 v138, s41, 8, v138
	v_ashrrev_i32_e32 v139, 31, v138
	v_lshl_add_u64 v[140:141], v[138:139], 2, s[10:11]
	global_load_dword v159, v[140:141], off
	global_load_dword v213, v[140:141], off offset:64
	global_load_dword v218, v[140:141], off offset:128
	global_load_dword v222, v[140:141], off offset:192
	global_load_dword v252, v[140:141], off offset:512
	global_load_dword v253, v[140:141], off offset:576
	global_load_dword v155, v[140:141], off offset:640
	global_load_dword v157, v[140:141], off offset:704
	v_readlane_b32 s18, v254, 12
	s_add_i32 s39, s39, 1
	v_readlane_b32 s19, v254, 13
	s_mul_i32 s6, s39, s19
	s_mul_hi_u32 s7, s39, s18
	s_add_i32 s7, s7, s6
	s_mul_i32 s6, s39, s18
	v_readlane_b32 s15, v254, 0
	s_add_u32 s18, s6, s15
	v_readlane_b32 s6, v254, 9
	s_addc_u32 s19, s7, s6
	v_cmp_gt_i64_e32 vcc, s[18:19], v[148:149]
	v_cmp_lt_i64_e64 s[6:7], s[18:19], v[146:147]
	s_cbranch_vccnz .LBB0_1294
	s_ashr_i32 s14, s18, 31
	s_lshr_b32 s14, s14, 29
	s_add_i32 s16, s18, s14
	s_and_b32 s14, s16, -8
	s_sub_i32 s17, s18, s14
	s_cmp_gt_i32 s17, 5
	s_mov_b64 s[14:15], -1
	s_cbranch_scc0 .LBB0_1291
	s_mul_i32 s14, s17, 0xbd
	s_add_i32 s18, s14, 6
	s_mov_b64 s[14:15], 0

; DI unsigned cvt_pk(float lo, float hi) { unsigned r; asm("v_cvt_pk_bf16_f32 %0, %1, %2" : "=v"(r) : "v"(lo), "v"(hi)); return r; }
; DI float siluf_(float x) { return x * sigmoidf_(x); }
;     __device__ __forceinline__ void operator()(const f32x4 (&acc)[2][2][4][2], const Unit& u, int wr, int wc, int fr, int fq) const {
;         const int row0 = u.pm * BM + wr * 64 + fr, col0 = u.pn * 128 + wc * 32 + 8 * fq;
; #pragma unroll
;         for (int ai = 0; ai < 2; ++ai)
; #pragma unroll
;             for (int m = 0; m < 4; ++m) {
;                 const int row = row0 + ai * HALF + m * 16;
;                 const float rs = rsqrtf(ss[row] * (1.f / DM) + EPS);
;                 float h[8];
; #pragma unroll
;                 for (int n = 0; n < 2; ++n)
; #pragma unroll
;                     for (int j = 0; j < 4; ++j) { const float gg = acc[ai][0][m][n][j] * rs, uu = acc[ai][1][m][n][j] * rs; h[4 * n + j] = siluf_(gg) * uu; }
;                 u32x4 w; w.x = cvt_pk(h[0], h[1]); w.y = cvt_pk(h[2], h[3]); w.z = cvt_pk(h[4], h[5]); w.w = cvt_pk(h[6], h[7]);
;                 *(u32x4*)(H + (size_t)row * DFF + col0) = w;
;             }
.LBB0_1298:
	v_lshrrev_b32_e32 v138, 8, v212
	v_and_b32_e32 v139, 15, v212
	v_lshl_or_b32 v138, v138, 6, v139
	v_lshl_add_u32 v138, s41, 8, v138
	s_mov_b32 s15, 0x800000
	v_lshrrev_b32_e32 v142, 6, v212
	v_and_b32_e32 v142, 3, v142
	v_lshrrev_b32_e32 v143, 1, v212
	v_and_b32_e32 v143, 24, v143
	v_lshl_or_b32 v142, v142, 5, v143
	v_lshl_or_b32 v142, s40, 7, v142
	v_ashrrev_i32_e32 v143, 31, v142
	v_mov_b64_e32 v[186:187], s[4:5]
	v_lshlrev_b64 v[188:189], 1, v[142:143]
	v_fmamk_f32 v180, v159, 0x3a800000, v217
	v_cmp_gt_f32_e32 vcc, s15, v180
	v_mul_f32_e32 v181, 0x4b800000, v180
	s_nop 0
	v_cndmask_b32_e32 v180, v180, v181, vcc
	v_rsq_f32_e32 v180, v180
	v_add_u32_e32 v182, 0, v138
	v_mul_f32_e32 v181, 0x45800000, v180
	v_cndmask_b32_e32 v180, v180, v181, vcc
	v_mul_f32_e32 v124, v124, v180
	v_mul_f32_e32 v120, v120, v180
	v_mul_f32_e32 v125, v125, v180
	v_mul_f32_e32 v121, v121, v180
	v_mul_f32_e32 v126, v126, v180
	v_mul_f32_e32 v122, v122, v180
	v_mul_f32_e32 v127, v127, v180
	v_mul_f32_e32 v123, v123, v180
	v_mul_f32_e32 v116, v116, v180
	v_mul_f32_e32 v112, v112, v180
	v_mul_f32_e32 v117, v117, v180
	v_mul_f32_e32 v113, v113, v180
	v_mul_f32_e32 v118, v118, v180
	v_mul_f32_e32 v114, v114, v180
	v_mul_f32_e32 v119, v119, v180
	v_mul_f32_e32 v115, v115, v180
	v_mul_f32_e32 v172, 0xbfb8aa3b, v124
	v_mul_f32_e32 v173, 0xbfb8aa3b, v125
	v_mul_f32_e32 v174, 0xbfb8aa3b, v126
	v_mul_f32_e32 v175, 0xbfb8aa3b, v127
	v_mul_f32_e32 v176, 0xbfb8aa3b, v116
	v_mul_f32_e32 v177, 0xbfb8aa3b, v117
	v_mul_f32_e32 v178, 0xbfb8aa3b, v118
	v_mul_f32_e32 v179, 0xbfb8aa3b, v119
	v_exp_f32_e32 v172, v172
	v_exp_f32_e32 v173, v173
	v_exp_f32_e32 v174, v174
	v_exp_f32_e32 v175, v175
	v_exp_f32_e32 v176, v176
	v_exp_f32_e32 v177, v177
	v_exp_f32_e32 v178, v178
	v_exp_f32_e32 v179, v179
	v_add_f32_e32 v172, 1.0, v172
	v_add_f32_e32 v173, 1.0, v173
	v_add_f32_e32 v174, 1.0, v174
	v_add_f32_e32 v175, 1.0, v175
	v_add_f32_e32 v176, 1.0, v176
	v_add_f32_e32 v177, 1.0, v177
	v_add_f32_e32 v178, 1.0, v178
	v_add_f32_e32 v179, 1.0, v179
	v_rcp_f32_e32 v172, v172
	v_rcp_f32_e32 v173, v173
	v_rcp_f32_e32 v174, v174
	v_rcp_f32_e32 v175, v175
	v_rcp_f32_e32 v176, v176
	v_rcp_f32_e32 v177, v177
	v_rcp_f32_e32 v178, v178
	v_rcp_f32_e32 v179, v179
	v_mul_f32_e32 v124, v124, v172
	v_mul_f32_e32 v125, v125, v173
	v_mul_f32_e32 v126, v126, v174
	v_mul_f32_e32 v127, v127, v175
	v_mul_f32_e32 v116, v116, v176
	v_mul_f32_e32 v117, v117, v177
	v_mul_f32_e32 v118, v118, v178
	v_mul_f32_e32 v119, v119, v179
	v_mul_f32_e32 v124, v120, v124
	v_mul_f32_e32 v125, v121, v125
	v_mul_f32_e32 v126, v122, v126
	v_mul_f32_e32 v127, v123, v127
	v_mul_f32_e32 v116, v112, v116
	v_mul_f32_e32 v117, v113, v117
	v_mul_f32_e32 v118, v114, v118
	v_mul_f32_e32 v119, v115, v119
	v_mad_i64_i32 v[184:185], s[22:23], v182, s64, v[186:187]
	v_cvt_pk_bf16_f32 v172, v124, v125
	v_cvt_pk_bf16_f32 v173, v126, v127
	v_cvt_pk_bf16_f32 v174, v116, v117
	v_cvt_pk_bf16_f32 v175, v118, v119
	v_lshl_add_u64 v[184:185], v[184:185], 0, v[188:189]
	global_store_dwordx4 v[184:185], v[172:175], off
	v_fmamk_f32 v180, v213, 0x3a800000, v217
	v_cmp_gt_f32_e32 vcc, s15, v180
	v_mul_f32_e32 v181, 0x4b800000, v180
	s_nop 0
	v_cndmask_b32_e32 v180, v180, v181, vcc
	v_rsq_f32_e32 v180, v180
	v_add_u32_e32 v182, 16, v138
	v_mul_f32_e32 v181, 0x45800000, v180
	v_cndmask_b32_e32 v180, v180, v181, vcc
	v_mul_f32_e32 v108, v108, v180
	v_mul_f32_e32 v104, v104, v180
	v_mul_f32_e32 v109, v109, v180
	v_mul_f32_e32 v105, v105, v180
	v_mul_f32_e32 v110, v110, v180
	v_mul_f32_e32 v106, v106, v180
	v_mul_f32_e32 v111, v111, v180
	v_mul_f32_e32 v107, v107, v180
	v_mul_f32_e32 v100, v100, v180
	v_mul_f32_e32 v96, v96, v180
	v_mul_f32_e32 v101, v101, v180
	v_mul_f32_e32 v97, v97, v180
	v_mul_f32_e32 v102, v102, v180
	v_mul_f32_e32 v98, v98, v180
	v_mul_f32_e32 v103, v103, v180
	v_mul_f32_e32 v99, v99, v180
	v_mul_f32_e32 v172, 0xbfb8aa3b, v108
	v_mul_f32_e32 v173, 0xbfb8aa3b, v109
	v_mul_f32_e32 v174, 0xbfb8aa3b, v110
	v_mul_f32_e32 v175, 0xbfb8aa3b, v111
	v_mul_f32_e32 v176, 0xbfb8aa3b, v100
	v_mul_f32_e32 v177, 0xbfb8aa3b, v101
	v_mul_f32_e32 v178, 0xbfb8aa3b, v102
	v_mul_f32_e32 v179, 0xbfb8aa3b, v103
	v_exp_f32_e32 v172, v172
	v_exp_f32_e32 v173, v173
	v_exp_f32_e32 v174, v174
	v_exp_f32_e32 v175, v175
	v_exp_f32_e32 v176, v176
	v_exp_f32_e32 v177, v177
	v_exp_f32_e32 v178, v178
	v_exp_f32_e32 v179, v179
	v_add_f32_e32 v172, 1.0, v172
	v_add_f32_e32 v173, 1.0, v173
	v_add_f32_e32 v174, 1.0, v174
	v_add_f32_e32 v175, 1.0, v175
	v_add_f32_e32 v176, 1.0, v176
	v_add_f32_e32 v177, 1.0, v177
	v_add_f32_e32 v178, 1.0, v178
	v_add_f32_e32 v179, 1.0, v179
	v_rcp_f32_e32 v172, v172
	v_rcp_f32_e32 v173, v173
	v_rcp_f32_e32 v174, v174
	v_rcp_f32_e32 v175, v175
	v_rcp_f32_e32 v176, v176
	v_rcp_f32_e32 v177, v177
	v_rcp_f32_e32 v178, v178
	v_rcp_f32_e32 v179, v179
	v_mul_f32_e32 v108, v108, v172
	v_mul_f32_e32 v109, v109, v173
	v_mul_f32_e32 v110, v110, v174
	v_mul_f32_e32 v111, v111, v175
	v_mul_f32_e32 v100, v100, v176
	v_mul_f32_e32 v101, v101, v177
	v_mul_f32_e32 v102, v102, v178
	v_mul_f32_e32 v103, v103, v179
	v_mul_f32_e32 v108, v104, v108
	v_mul_f32_e32 v109, v105, v109
	v_mul_f32_e32 v110, v106, v110
	v_mul_f32_e32 v111, v107, v111
	v_mul_f32_e32 v100, v96, v100
	v_mul_f32_e32 v101, v97, v101
	v_mul_f32_e32 v102, v98, v102
	v_mul_f32_e32 v103, v99, v103
	v_mad_i64_i32 v[184:185], s[22:23], v182, s64, v[186:187]
	v_cvt_pk_bf16_f32 v172, v108, v109
	v_cvt_pk_bf16_f32 v173, v110, v111
	v_cvt_pk_bf16_f32 v174, v100, v101
	v_cvt_pk_bf16_f32 v175, v102, v103
	v_lshl_add_u64 v[184:185], v[184:185], 0, v[188:189]
	global_store_dwordx4 v[184:185], v[172:175], off
; DI unsigned cvt_pk(float lo, float hi) { unsigned r; asm("v_cvt_pk_bf16_f32 %0, %1, %2" : "=v"(r) : "v"(lo), "v"(hi)); return r; }
; DI float siluf_(float x) { return x * sigmoidf_(x); }
;     __device__ __forceinline__ void operator()(const f32x4 (&acc)[2][2][4][2], const Unit& u, int wr, int wc, int fr, int fq) const {
;         const int row0 = u.pm * BM + wr * 64 + fr, col0 = u.pn * 128 + wc * 32 + 8 * fq;
; #pragma unroll
;         for (int ai = 0; ai < 2; ++ai)
; #pragma unroll
;             for (int m = 0; m < 4; ++m) {
;                 const int row = row0 + ai * HALF + m * 16;
;                 const float rs = rsqrtf(ss[row] * (1.f / DM) + EPS);
;                 float h[8];
; #pragma unroll
;                 for (int n = 0; n < 2; ++n)
; #pragma unroll
;                     for (int j = 0; j < 4; ++j) { const float gg = acc[ai][0][m][n][j] * rs, uu = acc[ai][1][m][n][j] * rs; h[4 * n + j] = siluf_(gg) * uu; }
;                 u32x4 w; w.x = cvt_pk(h[0], h[1]); w.y = cvt_pk(h[2], h[3]); w.z = cvt_pk(h[4], h[5]); w.w = cvt_pk(h[6], h[7]);
;                 *(u32x4*)(H + (size_t)row * DFF + col0) = w;
;             }
	v_fmamk_f32 v180, v218, 0x3a800000, v217
	v_cmp_gt_f32_e32 vcc, s15, v180
	v_mul_f32_e32 v181, 0x4b800000, v180
	s_nop 0
	v_cndmask_b32_e32 v180, v180, v181, vcc
	v_rsq_f32_e32 v180, v180
	v_add_u32_e32 v182, 32, v138
	v_mul_f32_e32 v181, 0x45800000, v180
	v_cndmask_b32_e32 v180, v180, v181, vcc
	v_mul_f32_e32 v92, v92, v180
	v_mul_f32_e32 v88, v88, v180
	v_mul_f32_e32 v93, v93, v180
	v_mul_f32_e32 v89, v89, v180
	v_mul_f32_e32 v94, v94, v180
	v_mul_f32_e32 v90, v90, v180
	v_mul_f32_e32 v95, v95, v180
	v_mul_f32_e32 v91, v91, v180
	v_mul_f32_e32 v84, v84, v180
	v_mul_f32_e32 v80, v80, v180
	v_mul_f32_e32 v85, v85, v180
	v_mul_f32_e32 v81, v81, v180
	v_mul_f32_e32 v86, v86, v180
	v_mul_f32_e32 v82, v82, v180
	v_mul_f32_e32 v87, v87, v180
	v_mul_f32_e32 v83, v83, v180
	v_mul_f32_e32 v172, 0xbfb8aa3b, v92
	v_mul_f32_e32 v173, 0xbfb8aa3b, v93
	v_mul_f32_e32 v174, 0xbfb8aa3b, v94
	v_mul_f32_e32 v175, 0xbfb8aa3b, v95
	v_mul_f32_e32 v176, 0xbfb8aa3b, v84
	v_mul_f32_e32 v177, 0xbfb8aa3b, v85
	v_mul_f32_e32 v178, 0xbfb8aa3b, v86
	v_mul_f32_e32 v179, 0xbfb8aa3b, v87
	v_exp_f32_e32 v172, v172
	v_exp_f32_e32 v173, v173
	v_exp_f32_e32 v174, v174
	v_exp_f32_e32 v175, v175
	v_exp_f32_e32 v176, v176
	v_exp_f32_e32 v177, v177
	v_exp_f32_e32 v178, v178
	v_exp_f32_e32 v179, v179
	v_add_f32_e32 v172, 1.0, v172
	v_add_f32_e32 v173, 1.0, v173
	v_add_f32_e32 v174, 1.0, v174
	v_add_f32_e32 v175, 1.0, v175
	v_add_f32_e32 v176, 1.0, v176
	v_add_f32_e32 v177, 1.0, v177
	v_add_f32_e32 v178, 1.0, v178
	v_add_f32_e32 v179, 1.0, v179
	v_rcp_f32_e32 v172, v172
	v_rcp_f32_e32 v173, v173
	v_rcp_f32_e32 v174, v174
	v_rcp_f32_e32 v175, v175
	v_rcp_f32_e32 v176, v176
	v_rcp_f32_e32 v177, v177
	v_rcp_f32_e32 v178, v178
	v_rcp_f32_e32 v179, v179
	v_mul_f32_e32 v92, v92, v172
	v_mul_f32_e32 v93, v93, v173
	v_mul_f32_e32 v94, v94, v174
	v_mul_f32_e32 v95, v95, v175
	v_mul_f32_e32 v84, v84, v176
	v_mul_f32_e32 v85, v85, v177
	v_mul_f32_e32 v86, v86, v178
	v_mul_f32_e32 v87, v87, v179
	v_mul_f32_e32 v92, v88, v92
	v_mul_f32_e32 v93, v89, v93
	v_mul_f32_e32 v94, v90, v94
	v_mul_f32_e32 v95, v91, v95
	v_mul_f32_e32 v84, v80, v84
	v_mul_f32_e32 v85, v81, v85
	v_mul_f32_e32 v86, v82, v86
	v_mul_f32_e32 v87, v83, v87
	v_mad_i64_i32 v[184:185], s[22:23], v182, s64, v[186:187]
	v_cvt_pk_bf16_f32 v172, v92, v93
	v_cvt_pk_bf16_f32 v173, v94, v95
	v_cvt_pk_bf16_f32 v174, v84, v85
	v_cvt_pk_bf16_f32 v175, v86, v87
	v_lshl_add_u64 v[184:185], v[184:185], 0, v[188:189]
	global_store_dwordx4 v[184:185], v[172:175], off
	v_fmamk_f32 v180, v222, 0x3a800000, v217
	v_cmp_gt_f32_e32 vcc, s15, v180
	v_mul_f32_e32 v181, 0x4b800000, v180
	s_nop 0
	v_cndmask_b32_e32 v180, v180, v181, vcc
	v_rsq_f32_e32 v180, v180
	v_add_u32_e32 v182, 48, v138
	v_mul_f32_e32 v181, 0x45800000, v180
	v_cndmask_b32_e32 v180, v180, v181, vcc
	v_mul_f32_e32 v76, v76, v180
	v_mul_f32_e32 v72, v72, v180
	v_mul_f32_e32 v77, v77, v180
	v_mul_f32_e32 v73, v73, v180
	v_mul_f32_e32 v78, v78, v180
	v_mul_f32_e32 v74, v74, v180
	v_mul_f32_e32 v79, v79, v180
	v_mul_f32_e32 v75, v75, v180
	v_mul_f32_e32 v68, v68, v180
	v_mul_f32_e32 v64, v64, v180
	v_mul_f32_e32 v69, v69, v180
	v_mul_f32_e32 v65, v65, v180
	v_mul_f32_e32 v70, v70, v180
	v_mul_f32_e32 v66, v66, v180
	v_mul_f32_e32 v71, v71, v180
	v_mul_f32_e32 v67, v67, v180
	v_mul_f32_e32 v172, 0xbfb8aa3b, v76
	v_mul_f32_e32 v173, 0xbfb8aa3b, v77
	v_mul_f32_e32 v174, 0xbfb8aa3b, v78
	v_mul_f32_e32 v175, 0xbfb8aa3b, v79
	v_mul_f32_e32 v176, 0xbfb8aa3b, v68
	v_mul_f32_e32 v177, 0xbfb8aa3b, v69
	v_mul_f32_e32 v178, 0xbfb8aa3b, v70
	v_mul_f32_e32 v179, 0xbfb8aa3b, v71
	v_exp_f32_e32 v172, v172
	v_exp_f32_e32 v173, v173
	v_exp_f32_e32 v174, v174
	v_exp_f32_e32 v175, v175
	v_exp_f32_e32 v176, v176
	v_exp_f32_e32 v177, v177
	v_exp_f32_e32 v178, v178
	v_exp_f32_e32 v179, v179
	v_add_f32_e32 v172, 1.0, v172
	v_add_f32_e32 v173, 1.0, v173
	v_add_f32_e32 v174, 1.0, v174
	v_add_f32_e32 v175, 1.0, v175
	v_add_f32_e32 v176, 1.0, v176
	v_add_f32_e32 v177, 1.0, v177
	v_add_f32_e32 v178, 1.0, v178
	v_add_f32_e32 v179, 1.0, v179
	v_rcp_f32_e32 v172, v172
	v_rcp_f32_e32 v173, v173
	v_rcp_f32_e32 v174, v174
	v_rcp_f32_e32 v175, v175
	v_rcp_f32_e32 v176, v176
	v_rcp_f32_e32 v177, v177
	v_rcp_f32_e32 v178, v178
	v_rcp_f32_e32 v179, v179
	v_mul_f32_e32 v76, v76, v172
	v_mul_f32_e32 v77, v77, v173
	v_mul_f32_e32 v78, v78, v174
	v_mul_f32_e32 v79, v79, v175
	v_mul_f32_e32 v68, v68, v176
	v_mul_f32_e32 v69, v69, v177
	v_mul_f32_e32 v70, v70, v178
	v_mul_f32_e32 v71, v71, v179
	v_mul_f32_e32 v76, v72, v76
	v_mul_f32_e32 v77, v73, v77
	v_mul_f32_e32 v78, v74, v78
	v_mul_f32_e32 v79, v75, v79
	v_mul_f32_e32 v68, v64, v68
	v_mul_f32_e32 v69, v65, v69
	v_mul_f32_e32 v70, v66, v70
	v_mul_f32_e32 v71, v67, v71
	v_mad_i64_i32 v[184:185], s[22:23], v182, s64, v[186:187]
	v_cvt_pk_bf16_f32 v172, v76, v77
	v_cvt_pk_bf16_f32 v173, v78, v79
	v_cvt_pk_bf16_f32 v174, v68, v69
	v_cvt_pk_bf16_f32 v175, v70, v71
	v_lshl_add_u64 v[184:185], v[184:185], 0, v[188:189]
	global_store_dwordx4 v[184:185], v[172:175], off
	v_fmamk_f32 v180, v252, 0x3a800000, v217
	v_cmp_gt_f32_e32 vcc, s15, v180
	v_mul_f32_e32 v181, 0x4b800000, v180
	s_nop 0
	v_cndmask_b32_e32 v180, v180, v181, vcc
	v_rsq_f32_e32 v180, v180
	v_add_u32_e32 v182, 128, v138
	v_mul_f32_e32 v181, 0x45800000, v180
	v_cndmask_b32_e32 v180, v180, v181, vcc
	v_mul_f32_e32 v60, v60, v180
	v_mul_f32_e32 v56, v56, v180
	v_mul_f32_e32 v61, v61, v180
	v_mul_f32_e32 v57, v57, v180
	v_mul_f32_e32 v62, v62, v180
	v_mul_f32_e32 v58, v58, v180
	v_mul_f32_e32 v63, v63, v180
	v_mul_f32_e32 v59, v59, v180
	v_mul_f32_e32 v52, v52, v180
	v_mul_f32_e32 v48, v48, v180
	v_mul_f32_e32 v53, v53, v180
; DI unsigned cvt_pk(float lo, float hi) { unsigned r; asm("v_cvt_pk_bf16_f32 %0, %1, %2" : "=v"(r) : "v"(lo), "v"(hi)); return r; }
; DI float siluf_(float x) { return x * sigmoidf_(x); }
;     __device__ __forceinline__ void operator()(const f32x4 (&acc)[2][2][4][2], const Unit& u, int wr, int wc, int fr, int fq) const {
;         const int row0 = u.pm * BM + wr * 64 + fr, col0 = u.pn * 128 + wc * 32 + 8 * fq;
; #pragma unroll
;         for (int ai = 0; ai < 2; ++ai)
; #pragma unroll
;             for (int m = 0; m < 4; ++m) {
;                 const int row = row0 + ai * HALF + m * 16;
;                 const float rs = rsqrtf(ss[row] * (1.f / DM) + EPS);
;                 float h[8];
; #pragma unroll
;                 for (int n = 0; n < 2; ++n)
; #pragma unroll
;                     for (int j = 0; j < 4; ++j) { const float gg = acc[ai][0][m][n][j] * rs, uu = acc[ai][1][m][n][j] * rs; h[4 * n + j] = siluf_(gg) * uu; }
;                 u32x4 w; w.x = cvt_pk(h[0], h[1]); w.y = cvt_pk(h[2], h[3]); w.z = cvt_pk(h[4], h[5]); w.w = cvt_pk(h[6], h[7]);
;                 *(u32x4*)(H + (size_t)row * DFF + col0) = w;
;             }
	v_mul_f32_e32 v49, v49, v180
	v_mul_f32_e32 v54, v54, v180
	v_mul_f32_e32 v50, v50, v180
	v_mul_f32_e32 v55, v55, v180
	v_mul_f32_e32 v51, v51, v180
	v_mul_f32_e32 v172, 0xbfb8aa3b, v60
	v_mul_f32_e32 v173, 0xbfb8aa3b, v61
	v_mul_f32_e32 v174, 0xbfb8aa3b, v62
	v_mul_f32_e32 v175, 0xbfb8aa3b, v63
	v_mul_f32_e32 v176, 0xbfb8aa3b, v52
	v_mul_f32_e32 v177, 0xbfb8aa3b, v53
	v_mul_f32_e32 v178, 0xbfb8aa3b, v54
	v_mul_f32_e32 v179, 0xbfb8aa3b, v55
	v_exp_f32_e32 v172, v172
	v_exp_f32_e32 v173, v173
	v_exp_f32_e32 v174, v174
	v_exp_f32_e32 v175, v175
	v_exp_f32_e32 v176, v176
	v_exp_f32_e32 v177, v177
	v_exp_f32_e32 v178, v178
	v_exp_f32_e32 v179, v179
	v_add_f32_e32 v172, 1.0, v172
	v_add_f32_e32 v173, 1.0, v173
	v_add_f32_e32 v174, 1.0, v174
	v_add_f32_e32 v175, 1.0, v175
	v_add_f32_e32 v176, 1.0, v176
	v_add_f32_e32 v177, 1.0, v177
	v_add_f32_e32 v178, 1.0, v178
	v_add_f32_e32 v179, 1.0, v179
	v_rcp_f32_e32 v172, v172
	v_rcp_f32_e32 v173, v173
	v_rcp_f32_e32 v174, v174
	v_rcp_f32_e32 v175, v175
	v_rcp_f32_e32 v176, v176
	v_rcp_f32_e32 v177, v177
	v_rcp_f32_e32 v178, v178
	v_rcp_f32_e32 v179, v179
	v_mul_f32_e32 v60, v60, v172
	v_mul_f32_e32 v61, v61, v173
	v_mul_f32_e32 v62, v62, v174
	v_mul_f32_e32 v63, v63, v175
	v_mul_f32_e32 v52, v52, v176
	v_mul_f32_e32 v53, v53, v177
	v_mul_f32_e32 v54, v54, v178
	v_mul_f32_e32 v55, v55, v179
	v_mul_f32_e32 v60, v56, v60
	v_mul_f32_e32 v61, v57, v61
	v_mul_f32_e32 v62, v58, v62
	v_mul_f32_e32 v63, v59, v63
	v_mul_f32_e32 v52, v48, v52
	v_mul_f32_e32 v53, v49, v53
	v_mul_f32_e32 v54, v50, v54
	v_mul_f32_e32 v55, v51, v55
	v_mad_i64_i32 v[184:185], s[22:23], v182, s64, v[186:187]
	v_cvt_pk_bf16_f32 v172, v60, v61
	v_cvt_pk_bf16_f32 v173, v62, v63
	v_cvt_pk_bf16_f32 v174, v52, v53
	v_cvt_pk_bf16_f32 v175, v54, v55
	v_lshl_add_u64 v[184:185], v[184:185], 0, v[188:189]
	global_store_dwordx4 v[184:185], v[172:175], off
	v_fmamk_f32 v180, v253, 0x3a800000, v217
	v_cmp_gt_f32_e32 vcc, s15, v180
	v_mul_f32_e32 v181, 0x4b800000, v180
	s_nop 0
	v_cndmask_b32_e32 v180, v180, v181, vcc
	v_rsq_f32_e32 v180, v180
	v_add_u32_e32 v182, 144, v138
	v_mul_f32_e32 v181, 0x45800000, v180
	v_cndmask_b32_e32 v180, v180, v181, vcc
	v_mul_f32_e32 v44, v44, v180
	v_mul_f32_e32 v40, v40, v180
	v_mul_f32_e32 v45, v45, v180
	v_mul_f32_e32 v41, v41, v180
	v_mul_f32_e32 v46, v46, v180
	v_mul_f32_e32 v42, v42, v180
	v_mul_f32_e32 v47, v47, v180
	v_mul_f32_e32 v43, v43, v180
	v_mul_f32_e32 v36, v36, v180
	v_mul_f32_e32 v32, v32, v180
	v_mul_f32_e32 v37, v37, v180
	v_mul_f32_e32 v33, v33, v180
	v_mul_f32_e32 v38, v38, v180
	v_mul_f32_e32 v34, v34, v180
	v_mul_f32_e32 v39, v39, v180
	v_mul_f32_e32 v35, v35, v180
	v_mul_f32_e32 v172, 0xbfb8aa3b, v44
	v_mul_f32_e32 v173, 0xbfb8aa3b, v45
	v_mul_f32_e32 v174, 0xbfb8aa3b, v46
	v_mul_f32_e32 v175, 0xbfb8aa3b, v47
	v_mul_f32_e32 v176, 0xbfb8aa3b, v36
	v_mul_f32_e32 v177, 0xbfb8aa3b, v37
	v_mul_f32_e32 v178, 0xbfb8aa3b, v38
	v_mul_f32_e32 v179, 0xbfb8aa3b, v39
	v_exp_f32_e32 v172, v172
	v_exp_f32_e32 v173, v173
	v_exp_f32_e32 v174, v174
	v_exp_f32_e32 v175, v175
	v_exp_f32_e32 v176, v176
	v_exp_f32_e32 v177, v177
	v_exp_f32_e32 v178, v178
	v_exp_f32_e32 v179, v179
	v_add_f32_e32 v172, 1.0, v172
	v_add_f32_e32 v173, 1.0, v173
	v_add_f32_e32 v174, 1.0, v174
	v_add_f32_e32 v175, 1.0, v175
	v_add_f32_e32 v176, 1.0, v176
	v_add_f32_e32 v177, 1.0, v177
	v_add_f32_e32 v178, 1.0, v178
	v_add_f32_e32 v179, 1.0, v179
	v_rcp_f32_e32 v172, v172
	v_rcp_f32_e32 v173, v173
	v_rcp_f32_e32 v174, v174
	v_rcp_f32_e32 v175, v175
	v_rcp_f32_e32 v176, v176
	v_rcp_f32_e32 v177, v177
	v_rcp_f32_e32 v178, v178
	v_rcp_f32_e32 v179, v179
	v_mul_f32_e32 v44, v44, v172
	v_mul_f32_e32 v45, v45, v173
	v_mul_f32_e32 v46, v46, v174
	v_mul_f32_e32 v47, v47, v175
	v_mul_f32_e32 v36, v36, v176
	v_mul_f32_e32 v37, v37, v177
	v_mul_f32_e32 v38, v38, v178
	v_mul_f32_e32 v39, v39, v179
	v_mul_f32_e32 v44, v40, v44
	v_mul_f32_e32 v45, v41, v45
	v_mul_f32_e32 v46, v42, v46
	v_mul_f32_e32 v47, v43, v47
	v_mul_f32_e32 v36, v32, v36
	v_mul_f32_e32 v37, v33, v37
	v_mul_f32_e32 v38, v34, v38
	v_mul_f32_e32 v39, v35, v39
	v_mad_i64_i32 v[184:185], s[22:23], v182, s64, v[186:187]
	v_cvt_pk_bf16_f32 v172, v44, v45
	v_cvt_pk_bf16_f32 v173, v46, v47
	v_cvt_pk_bf16_f32 v174, v36, v37
	v_cvt_pk_bf16_f32 v175, v38, v39
	v_lshl_add_u64 v[184:185], v[184:185], 0, v[188:189]
	global_store_dwordx4 v[184:185], v[172:175], off
	v_fmamk_f32 v180, v155, 0x3a800000, v217
	v_cmp_gt_f32_e32 vcc, s15, v180
	v_mul_f32_e32 v181, 0x4b800000, v180
	s_nop 0
	v_cndmask_b32_e32 v180, v180, v181, vcc
	v_rsq_f32_e32 v180, v180
	v_add_u32_e32 v182, 160, v138
	v_mul_f32_e32 v181, 0x45800000, v180
	v_cndmask_b32_e32 v180, v180, v181, vcc
	v_mul_f32_e32 v28, v28, v180
	v_mul_f32_e32 v24, v24, v180
	v_mul_f32_e32 v29, v29, v180
; DI unsigned cvt_pk(float lo, float hi) { unsigned r; asm("v_cvt_pk_bf16_f32 %0, %1, %2" : "=v"(r) : "v"(lo), "v"(hi)); return r; }
; DI float siluf_(float x) { return x * sigmoidf_(x); }
;     __device__ __forceinline__ void operator()(const f32x4 (&acc)[2][2][4][2], const Unit& u, int wr, int wc, int fr, int fq) const {
;         const int row0 = u.pm * BM + wr * 64 + fr, col0 = u.pn * 128 + wc * 32 + 8 * fq;
; #pragma unroll
;         for (int ai = 0; ai < 2; ++ai)
; #pragma unroll
;             for (int m = 0; m < 4; ++m) {
;                 const int row = row0 + ai * HALF + m * 16;
;                 const float rs = rsqrtf(ss[row] * (1.f / DM) + EPS);
;                 float h[8];
; #pragma unroll
;                 for (int n = 0; n < 2; ++n)
; #pragma unroll
;                     for (int j = 0; j < 4; ++j) { const float gg = acc[ai][0][m][n][j] * rs, uu = acc[ai][1][m][n][j] * rs; h[4 * n + j] = siluf_(gg) * uu; }
;                 u32x4 w; w.x = cvt_pk(h[0], h[1]); w.y = cvt_pk(h[2], h[3]); w.z = cvt_pk(h[4], h[5]); w.w = cvt_pk(h[6], h[7]);
;                 *(u32x4*)(H + (size_t)row * DFF + col0) = w;
;             }
	v_mul_f32_e32 v25, v25, v180
	v_mul_f32_e32 v30, v30, v180
	v_mul_f32_e32 v26, v26, v180
	v_mul_f32_e32 v31, v31, v180
	v_mul_f32_e32 v27, v27, v180
	v_mul_f32_e32 v20, v20, v180
	v_mul_f32_e32 v16, v16, v180
	v_mul_f32_e32 v21, v21, v180
	v_mul_f32_e32 v17, v17, v180
	v_mul_f32_e32 v22, v22, v180
	v_mul_f32_e32 v18, v18, v180
	v_mul_f32_e32 v23, v23, v180
	v_mul_f32_e32 v19, v19, v180
	v_mul_f32_e32 v172, 0xbfb8aa3b, v28
	v_mul_f32_e32 v173, 0xbfb8aa3b, v29
	v_mul_f32_e32 v174, 0xbfb8aa3b, v30
	v_mul_f32_e32 v175, 0xbfb8aa3b, v31
	v_mul_f32_e32 v176, 0xbfb8aa3b, v20
	v_mul_f32_e32 v177, 0xbfb8aa3b, v21
	v_mul_f32_e32 v178, 0xbfb8aa3b, v22
	v_mul_f32_e32 v179, 0xbfb8aa3b, v23
	v_exp_f32_e32 v172, v172
	v_exp_f32_e32 v173, v173
	v_exp_f32_e32 v174, v174
	v_exp_f32_e32 v175, v175
	v_exp_f32_e32 v176, v176
	v_exp_f32_e32 v177, v177
	v_exp_f32_e32 v178, v178
	v_exp_f32_e32 v179, v179
	v_add_f32_e32 v172, 1.0, v172
	v_add_f32_e32 v173, 1.0, v173
	v_add_f32_e32 v174, 1.0, v174
	v_add_f32_e32 v175, 1.0, v175
	v_add_f32_e32 v176, 1.0, v176
	v_add_f32_e32 v177, 1.0, v177
	v_add_f32_e32 v178, 1.0, v178
	v_add_f32_e32 v179, 1.0, v179
	v_rcp_f32_e32 v172, v172
	v_rcp_f32_e32 v173, v173
	v_rcp_f32_e32 v174, v174
	v_rcp_f32_e32 v175, v175
	v_rcp_f32_e32 v176, v176
	v_rcp_f32_e32 v177, v177
	v_rcp_f32_e32 v178, v178
	v_rcp_f32_e32 v179, v179
	v_mul_f32_e32 v28, v28, v172
	v_mul_f32_e32 v29, v29, v173
	v_mul_f32_e32 v30, v30, v174
	v_mul_f32_e32 v31, v31, v175
	v_mul_f32_e32 v20, v20, v176
	v_mul_f32_e32 v21, v21, v177
	v_mul_f32_e32 v22, v22, v178
	v_mul_f32_e32 v23, v23, v179
	v_mul_f32_e32 v28, v24, v28
	v_mul_f32_e32 v29, v25, v29
	v_mul_f32_e32 v30, v26, v30
	v_mul_f32_e32 v31, v27, v31
	v_mul_f32_e32 v20, v16, v20
	v_mul_f32_e32 v21, v17, v21
	v_mul_f32_e32 v22, v18, v22
	v_mul_f32_e32 v23, v19, v23
	v_mad_i64_i32 v[184:185], s[22:23], v182, s64, v[186:187]
	v_cvt_pk_bf16_f32 v172, v28, v29
	v_cvt_pk_bf16_f32 v173, v30, v31
	v_cvt_pk_bf16_f32 v174, v20, v21
	v_cvt_pk_bf16_f32 v175, v22, v23
	v_lshl_add_u64 v[184:185], v[184:185], 0, v[188:189]
	global_store_dwordx4 v[184:185], v[172:175], off
	v_fmamk_f32 v180, v157, 0x3a800000, v217
	v_cmp_gt_f32_e32 vcc, s15, v180
	v_mul_f32_e32 v181, 0x4b800000, v180
	s_nop 0
	v_cndmask_b32_e32 v180, v180, v181, vcc
	v_rsq_f32_e32 v180, v180
	v_add_u32_e32 v182, 176, v138
	v_mul_f32_e32 v181, 0x45800000, v180
	v_cndmask_b32_e32 v180, v180, v181, vcc
	v_mul_f32_e32 v12, v12, v180
	v_mul_f32_e32 v8, v8, v180
	v_mul_f32_e32 v13, v13, v180
	v_mul_f32_e32 v9, v9, v180
	v_mul_f32_e32 v14, v14, v180
	v_mul_f32_e32 v10, v10, v180
	v_mul_f32_e32 v15, v15, v180
	v_mul_f32_e32 v11, v11, v180
	v_mul_f32_e32 v4, v4, v180
	v_mul_f32_e32 v0, v0, v180
	v_mul_f32_e32 v5, v5, v180
	v_mul_f32_e32 v1, v1, v180
	v_mul_f32_e32 v6, v6, v180
	v_mul_f32_e32 v2, v2, v180
	v_mul_f32_e32 v7, v7, v180
	v_mul_f32_e32 v3, v3, v180
	v_mul_f32_e32 v172, 0xbfb8aa3b, v12
	v_mul_f32_e32 v173, 0xbfb8aa3b, v13
	v_mul_f32_e32 v174, 0xbfb8aa3b, v14
	v_mul_f32_e32 v175, 0xbfb8aa3b, v15
	v_mul_f32_e32 v176, 0xbfb8aa3b, v4
	v_mul_f32_e32 v177, 0xbfb8aa3b, v5
	v_mul_f32_e32 v178, 0xbfb8aa3b, v6
	v_mul_f32_e32 v179, 0xbfb8aa3b, v7
	v_exp_f32_e32 v172, v172
	v_exp_f32_e32 v173, v173
	v_exp_f32_e32 v174, v174
	v_exp_f32_e32 v175, v175
	v_exp_f32_e32 v176, v176
	v_exp_f32_e32 v177, v177
	v_exp_f32_e32 v178, v178
	v_exp_f32_e32 v179, v179
	v_add_f32_e32 v172, 1.0, v172
	v_add_f32_e32 v173, 1.0, v173
	v_add_f32_e32 v174, 1.0, v174
	v_add_f32_e32 v175, 1.0, v175
	v_add_f32_e32 v176, 1.0, v176
	v_add_f32_e32 v177, 1.0, v177
	v_add_f32_e32 v178, 1.0, v178
	v_add_f32_e32 v179, 1.0, v179
	v_rcp_f32_e32 v172, v172
	v_rcp_f32_e32 v173, v173
	v_rcp_f32_e32 v174, v174
	v_rcp_f32_e32 v175, v175
	v_rcp_f32_e32 v176, v176
	v_rcp_f32_e32 v177, v177
	v_rcp_f32_e32 v178, v178
	v_rcp_f32_e32 v179, v179
	v_mul_f32_e32 v12, v12, v172
	v_mul_f32_e32 v13, v13, v173
	v_mul_f32_e32 v14, v14, v174
	v_mul_f32_e32 v15, v15, v175
	v_mul_f32_e32 v4, v4, v176
	v_mul_f32_e32 v5, v5, v177
	v_mul_f32_e32 v6, v6, v178
	v_mul_f32_e32 v7, v7, v179
	v_mul_f32_e32 v12, v8, v12
	v_mul_f32_e32 v13, v9, v13
	v_mul_f32_e32 v14, v10, v14
	v_mul_f32_e32 v15, v11, v15
	v_mul_f32_e32 v4, v0, v4
	v_mul_f32_e32 v5, v1, v5
	v_mul_f32_e32 v6, v2, v6
	v_mul_f32_e32 v7, v3, v7
	v_mad_i64_i32 v[184:185], s[22:23], v182, s64, v[186:187]
	v_cvt_pk_bf16_f32 v172, v12, v13
	v_cvt_pk_bf16_f32 v173, v14, v15
	v_cvt_pk_bf16_f32 v174, v4, v5
	v_cvt_pk_bf16_f32 v175, v6, v7
	v_lshl_add_u64 v[184:185], v[184:185], 0, v[188:189]
	global_store_dwordx4 v[184:185], v[172:175], off
	s_mov_b64 s[22:23], -1
	s_andn2_b64 vcc, exec, s[6:7]
	s_cbranch_vccnz .LBB0_1287
	s_andn2_b64 vcc, exec, s[2:3]
	s_cbranch_vccnz .LBB0_1286
	s_barrier
	s_branch .LBB0_1286
